# combined candidate + v_rsq_f32 in the in-proj q/k-norm epilogue (8 exact sqrt+div expansions per normed tile removed)
# speedup vs baseline: 1.0070x; 1.0051x over previous
.LBB0_182:
	s_waitcnt vmcnt(0)
	v_pk_mul_f32 v[130:131], v[128:129], v[184:185] op_sel_hi:[1,0]
	v_pk_mul_f32 v[132:133], v[126:127], v[184:185] op_sel_hi:[1,0]
	v_pk_mul_f32 v[134:135], v[124:125], v[184:185] op_sel_hi:[1,0]
	v_pk_mul_f32 v[136:137], v[122:123], v[184:185] op_sel_hi:[1,0]
	v_pk_mul_f32 v[212:213], v[120:121], v[184:185] op_sel_hi:[1,0]
	v_pk_mul_f32 v[214:215], v[118:119], v[184:185] op_sel_hi:[1,0]
	v_pk_mul_f32 v[208:209], v[116:117], v[184:185] op_sel_hi:[1,0]
	v_pk_mul_f32 v[210:211], v[114:115], v[184:185] op_sel_hi:[1,0]
	s_and_b64 vcc, exec, s[0:1]
	v_mov_b32_e32 v216, 1.0
	s_cbranch_vccnz .LBB0_184
	v_pk_mul_f32 v[204:205], v[130:131], v[130:131]
	v_pk_mul_f32 v[206:207], v[132:133], v[132:133]
	v_and_b32_e32 v169, 64, v230
	v_pk_mov_b32 v[216:217], v[206:207], v[204:205] op_sel:[1,0]
	v_mov_b32_e32 v207, v205
	v_pk_add_f32 v[204:205], v[216:217], v[206:207]
	v_pk_mul_f32 v[206:207], v[134:135], v[134:135]
	v_pk_add_f32 v[204:205], v[204:205], v[204:205] op_sel_hi:[0,1]
	v_pk_mul_f32 v[216:217], v[136:137], v[136:137]
	v_mul_f32_e32 v204, v214, v214
	v_pk_mov_b32 v[218:219], v[216:217], v[206:207] op_sel:[1,0]
	v_mov_b32_e32 v217, v207
	v_pk_add_f32 v[206:207], v[218:219], v[216:217]
	v_pk_fma_f32 v[216:217], v[214:215], v[214:215], v[204:205] op_sel_hi:[1,1,0]
	v_mul_f32_e32 v204, v212, v212
	v_pk_add_f32 v[206:207], v[206:207], v[206:207] op_sel_hi:[0,1]
	v_pk_fma_f32 v[218:219], v[212:213], v[212:213], v[204:205] op_sel_hi:[1,1,0]
	v_mul_f32_e32 v216, v210, v210
	v_mul_f32_e32 v218, v211, v211
	v_mul_f32_e32 v204, v208, v208
	v_mul_f32_e32 v206, v209, v209
	v_xor_b32_e32 v165, 16, v230
	v_add_u32_e32 v169, 64, v169
	v_pk_add_f32 v[216:217], v[216:217], v[218:219]
	v_pk_add_f32 v[204:205], v[204:205], v[206:207]
	v_cmp_lt_i32_e32 vcc, v165, v169
	v_pk_add_f32 v[204:205], v[216:217], v[204:205]
	s_nop 0
	v_cndmask_b32_e32 v165, v230, v165, vcc
	v_add_f32_e32 v161, v204, v205
	v_lshlrev_b32_e32 v165, 2, v165
	ds_bpermute_b32 v165, v165, v161
	s_waitcnt lgkmcnt(0)
	v_add_f32_e32 v161, v161, v165
	v_xor_b32_e32 v165, 32, v230
	v_cmp_lt_i32_e32 vcc, v165, v169
	s_nop 1
	v_cndmask_b32_e32 v165, v230, v165, vcc
	v_lshlrev_b32_e32 v165, 2, v165
	ds_bpermute_b32 v165, v165, v161
	s_waitcnt lgkmcnt(0)
	v_add_f32_e32 v161, v161, v165
	v_fmamk_f32 v161, v161, 0x3c800000, v226
	v_rsq_f32_e32 v216, v161
	s_nop 0

.LBB0_188:
	s_nop 0
	v_pk_mul_f32 v[130:131], v[112:113], v[180:181] op_sel_hi:[1,0]
	v_pk_mul_f32 v[132:133], v[110:111], v[180:181] op_sel_hi:[1,0]
	v_pk_mul_f32 v[134:135], v[108:109], v[180:181] op_sel_hi:[1,0]
	v_pk_mul_f32 v[136:137], v[106:107], v[180:181] op_sel_hi:[1,0]
	v_pk_mul_f32 v[212:213], v[104:105], v[180:181] op_sel_hi:[1,0]
	v_pk_mul_f32 v[214:215], v[102:103], v[180:181] op_sel_hi:[1,0]
	v_pk_mul_f32 v[208:209], v[100:101], v[180:181] op_sel_hi:[1,0]
	v_pk_mul_f32 v[210:211], v[98:99], v[180:181] op_sel_hi:[1,0]
	s_and_b64 vcc, exec, s[0:1]
	v_mov_b32_e32 v220, 1.0
	s_cbranch_vccnz .LBB0_190
	v_pk_mul_f32 v[216:217], v[130:131], v[130:131]
	v_pk_mul_f32 v[218:219], v[132:133], v[132:133]
	v_and_b32_e32 v169, 64, v230
	v_pk_mov_b32 v[220:221], v[218:219], v[216:217] op_sel:[1,0]
	v_mov_b32_e32 v219, v217
	v_pk_add_f32 v[216:217], v[220:221], v[218:219]
	v_pk_mul_f32 v[218:219], v[134:135], v[134:135]
	v_pk_add_f32 v[216:217], v[216:217], v[216:217] op_sel_hi:[0,1]
	v_pk_mul_f32 v[220:221], v[136:137], v[136:137]
	v_mul_f32_e32 v216, v214, v214
	v_pk_mov_b32 v[232:233], v[220:221], v[218:219] op_sel:[1,0]
	v_mov_b32_e32 v221, v219
	v_pk_add_f32 v[218:219], v[232:233], v[220:221]
	v_pk_fma_f32 v[220:221], v[214:215], v[214:215], v[216:217] op_sel_hi:[1,1,0]
	v_mul_f32_e32 v216, v212, v212
	v_pk_add_f32 v[218:219], v[218:219], v[218:219] op_sel_hi:[0,1]
	v_pk_fma_f32 v[232:233], v[212:213], v[212:213], v[216:217] op_sel_hi:[1,1,0]
	v_mul_f32_e32 v220, v210, v210
	v_mul_f32_e32 v232, v211, v211
	v_mul_f32_e32 v216, v208, v208
	v_mul_f32_e32 v218, v209, v209
	v_xor_b32_e32 v165, 16, v230
	v_add_u32_e32 v169, 64, v169
	v_pk_add_f32 v[220:221], v[220:221], v[232:233]
	v_pk_add_f32 v[216:217], v[216:217], v[218:219]
	v_cmp_lt_i32_e32 vcc, v165, v169
	v_pk_add_f32 v[216:217], v[220:221], v[216:217]
	s_nop 0
	v_cndmask_b32_e32 v165, v230, v165, vcc
	v_add_f32_e32 v161, v216, v217
	v_lshlrev_b32_e32 v165, 2, v165
	ds_bpermute_b32 v165, v165, v161
	s_waitcnt lgkmcnt(0)
	v_add_f32_e32 v161, v161, v165
	v_xor_b32_e32 v165, 32, v230
	v_cmp_lt_i32_e32 vcc, v165, v169
	s_nop 1
	v_cndmask_b32_e32 v165, v230, v165, vcc
	v_lshlrev_b32_e32 v165, 2, v165
	ds_bpermute_b32 v165, v165, v161
	s_waitcnt lgkmcnt(0)
	v_add_f32_e32 v161, v161, v165
	v_fmamk_f32 v161, v161, 0x3c800000, v226
	v_rsq_f32_e32 v220, v161
	s_nop 0

.LBB0_194:
	s_nop 0
	v_pk_mul_f32 v[130:131], v[96:97], v[176:177] op_sel_hi:[1,0]
	v_pk_mul_f32 v[132:133], v[94:95], v[176:177] op_sel_hi:[1,0]
	v_pk_mul_f32 v[134:135], v[92:93], v[176:177] op_sel_hi:[1,0]
	v_pk_mul_f32 v[136:137], v[90:91], v[176:177] op_sel_hi:[1,0]
	v_pk_mul_f32 v[212:213], v[88:89], v[176:177] op_sel_hi:[1,0]
	v_pk_mul_f32 v[214:215], v[86:87], v[176:177] op_sel_hi:[1,0]
	v_pk_mul_f32 v[208:209], v[84:85], v[176:177] op_sel_hi:[1,0]
	v_pk_mul_f32 v[210:211], v[82:83], v[176:177] op_sel_hi:[1,0]
	s_and_b64 vcc, exec, s[0:1]
	v_mov_b32_e32 v220, 1.0
	s_cbranch_vccnz .LBB0_196
	v_pk_mul_f32 v[216:217], v[130:131], v[130:131]
	v_pk_mul_f32 v[218:219], v[132:133], v[132:133]
	v_and_b32_e32 v169, 64, v230
	v_pk_mov_b32 v[220:221], v[218:219], v[216:217] op_sel:[1,0]
	v_mov_b32_e32 v219, v217
	v_pk_add_f32 v[216:217], v[220:221], v[218:219]
	v_pk_mul_f32 v[218:219], v[134:135], v[134:135]
	v_pk_add_f32 v[216:217], v[216:217], v[216:217] op_sel_hi:[0,1]
	v_pk_mul_f32 v[220:221], v[136:137], v[136:137]
	v_mul_f32_e32 v216, v214, v214
	v_pk_mov_b32 v[232:233], v[220:221], v[218:219] op_sel:[1,0]
	v_mov_b32_e32 v221, v219
	v_pk_add_f32 v[218:219], v[232:233], v[220:221]
	v_pk_fma_f32 v[220:221], v[214:215], v[214:215], v[216:217] op_sel_hi:[1,1,0]
	v_mul_f32_e32 v216, v212, v212
	v_pk_add_f32 v[218:219], v[218:219], v[218:219] op_sel_hi:[0,1]
	v_pk_fma_f32 v[232:233], v[212:213], v[212:213], v[216:217] op_sel_hi:[1,1,0]
	v_mul_f32_e32 v220, v210, v210
	v_mul_f32_e32 v232, v211, v211
	v_mul_f32_e32 v216, v208, v208
	v_mul_f32_e32 v218, v209, v209
	v_xor_b32_e32 v165, 16, v230
	v_add_u32_e32 v169, 64, v169
	v_pk_add_f32 v[220:221], v[220:221], v[232:233]
	v_pk_add_f32 v[216:217], v[216:217], v[218:219]
	v_cmp_lt_i32_e32 vcc, v165, v169
	v_pk_add_f32 v[216:217], v[220:221], v[216:217]
	s_nop 0
	v_cndmask_b32_e32 v165, v230, v165, vcc
	v_add_f32_e32 v161, v216, v217
	v_lshlrev_b32_e32 v165, 2, v165
	ds_bpermute_b32 v165, v165, v161
	s_waitcnt lgkmcnt(0)
	v_add_f32_e32 v161, v161, v165
	v_xor_b32_e32 v165, 32, v230
	v_cmp_lt_i32_e32 vcc, v165, v169
	s_nop 1
	v_cndmask_b32_e32 v165, v230, v165, vcc
	v_lshlrev_b32_e32 v165, 2, v165
	ds_bpermute_b32 v165, v165, v161
	s_waitcnt lgkmcnt(0)
	v_add_f32_e32 v161, v161, v165
	v_fmamk_f32 v161, v161, 0x3c800000, v226
	v_rsq_f32_e32 v220, v161
	s_nop 0

.LBB0_200:
	s_nop 0
	v_pk_mul_f32 v[130:131], v[80:81], v[172:173] op_sel_hi:[1,0]
	v_pk_mul_f32 v[132:133], v[78:79], v[172:173] op_sel_hi:[1,0]
	v_pk_mul_f32 v[134:135], v[76:77], v[172:173] op_sel_hi:[1,0]
	v_pk_mul_f32 v[136:137], v[74:75], v[172:173] op_sel_hi:[1,0]
	v_pk_mul_f32 v[212:213], v[72:73], v[172:173] op_sel_hi:[1,0]
	v_pk_mul_f32 v[214:215], v[70:71], v[172:173] op_sel_hi:[1,0]
	v_pk_mul_f32 v[208:209], v[68:69], v[172:173] op_sel_hi:[1,0]
	v_pk_mul_f32 v[210:211], v[66:67], v[172:173] op_sel_hi:[1,0]
	s_and_b64 vcc, exec, s[0:1]
	v_mov_b32_e32 v220, 1.0
	s_cbranch_vccnz .LBB0_202
	v_pk_mul_f32 v[216:217], v[130:131], v[130:131]
	v_pk_mul_f32 v[218:219], v[132:133], v[132:133]
	v_and_b32_e32 v169, 64, v230
	v_pk_mov_b32 v[220:221], v[218:219], v[216:217] op_sel:[1,0]
	v_mov_b32_e32 v219, v217
	v_pk_add_f32 v[216:217], v[220:221], v[218:219]
	v_pk_mul_f32 v[218:219], v[134:135], v[134:135]
	v_pk_add_f32 v[216:217], v[216:217], v[216:217] op_sel_hi:[0,1]
	v_pk_mul_f32 v[220:221], v[136:137], v[136:137]
	v_mul_f32_e32 v216, v214, v214
	v_pk_mov_b32 v[232:233], v[220:221], v[218:219] op_sel:[1,0]
	v_mov_b32_e32 v221, v219
	v_pk_add_f32 v[218:219], v[232:233], v[220:221]
	v_pk_fma_f32 v[220:221], v[214:215], v[214:215], v[216:217] op_sel_hi:[1,1,0]
	v_mul_f32_e32 v216, v212, v212
	v_pk_add_f32 v[218:219], v[218:219], v[218:219] op_sel_hi:[0,1]
	v_pk_fma_f32 v[232:233], v[212:213], v[212:213], v[216:217] op_sel_hi:[1,1,0]
	v_mul_f32_e32 v220, v210, v210
	v_mul_f32_e32 v232, v211, v211
	v_mul_f32_e32 v216, v208, v208
	v_mul_f32_e32 v218, v209, v209
	v_xor_b32_e32 v165, 16, v230
	v_add_u32_e32 v169, 64, v169
	v_pk_add_f32 v[220:221], v[220:221], v[232:233]
	v_pk_add_f32 v[216:217], v[216:217], v[218:219]
	v_cmp_lt_i32_e32 vcc, v165, v169
	v_pk_add_f32 v[216:217], v[220:221], v[216:217]
	s_nop 0
	v_cndmask_b32_e32 v165, v230, v165, vcc
	v_add_f32_e32 v161, v216, v217
	v_lshlrev_b32_e32 v165, 2, v165
	ds_bpermute_b32 v165, v165, v161
	s_waitcnt lgkmcnt(0)
	v_add_f32_e32 v161, v161, v165
	v_xor_b32_e32 v165, 32, v230
	v_cmp_lt_i32_e32 vcc, v165, v169
	s_nop 1
	v_cndmask_b32_e32 v165, v230, v165, vcc
	v_lshlrev_b32_e32 v165, 2, v165
	ds_bpermute_b32 v165, v165, v161
	s_waitcnt lgkmcnt(0)
	v_add_f32_e32 v161, v161, v165
	v_fmamk_f32 v161, v161, 0x3c800000, v226
	v_rsq_f32_e32 v220, v161
	s_nop 0

.LBB0_206:
	s_nop 0
	v_pk_mul_f32 v[130:131], v[64:65], v[168:169] op_sel_hi:[1,0]
	v_pk_mul_f32 v[132:133], v[62:63], v[168:169] op_sel_hi:[1,0]
	v_pk_mul_f32 v[134:135], v[60:61], v[168:169] op_sel_hi:[1,0]
	v_pk_mul_f32 v[136:137], v[58:59], v[168:169] op_sel_hi:[1,0]
	v_pk_mul_f32 v[212:213], v[56:57], v[168:169] op_sel_hi:[1,0]
	v_pk_mul_f32 v[214:215], v[54:55], v[168:169] op_sel_hi:[1,0]
	v_pk_mul_f32 v[208:209], v[52:53], v[168:169] op_sel_hi:[1,0]
	v_pk_mul_f32 v[210:211], v[50:51], v[168:169] op_sel_hi:[1,0]
	s_and_b64 vcc, exec, s[0:1]
	v_mov_b32_e32 v220, 1.0
	s_cbranch_vccnz .LBB0_208
	v_pk_mul_f32 v[216:217], v[130:131], v[130:131]
	v_pk_mul_f32 v[218:219], v[132:133], v[132:133]
	v_and_b32_e32 v169, 64, v230
	v_pk_mov_b32 v[220:221], v[218:219], v[216:217] op_sel:[1,0]
	v_mov_b32_e32 v219, v217
	v_pk_add_f32 v[216:217], v[220:221], v[218:219]
	v_pk_mul_f32 v[218:219], v[134:135], v[134:135]
	v_pk_add_f32 v[216:217], v[216:217], v[216:217] op_sel_hi:[0,1]
	v_pk_mul_f32 v[220:221], v[136:137], v[136:137]
	v_mul_f32_e32 v216, v214, v214
	v_pk_mov_b32 v[232:233], v[220:221], v[218:219] op_sel:[1,0]
	v_mov_b32_e32 v221, v219
	v_pk_add_f32 v[218:219], v[232:233], v[220:221]
	v_pk_fma_f32 v[220:221], v[214:215], v[214:215], v[216:217] op_sel_hi:[1,1,0]
	v_mul_f32_e32 v216, v212, v212
	v_pk_add_f32 v[218:219], v[218:219], v[218:219] op_sel_hi:[0,1]
	v_pk_fma_f32 v[232:233], v[212:213], v[212:213], v[216:217] op_sel_hi:[1,1,0]
	v_mul_f32_e32 v220, v210, v210
	v_mul_f32_e32 v232, v211, v211
	v_mul_f32_e32 v216, v208, v208
	v_mul_f32_e32 v218, v209, v209
	v_xor_b32_e32 v165, 16, v230
	v_add_u32_e32 v169, 64, v169
	v_pk_add_f32 v[220:221], v[220:221], v[232:233]
	v_pk_add_f32 v[216:217], v[216:217], v[218:219]
	v_cmp_lt_i32_e32 vcc, v165, v169
	v_pk_add_f32 v[216:217], v[220:221], v[216:217]
	s_nop 0
	v_cndmask_b32_e32 v165, v230, v165, vcc
	v_add_f32_e32 v161, v216, v217
	v_lshlrev_b32_e32 v165, 2, v165
	ds_bpermute_b32 v165, v165, v161
	s_waitcnt lgkmcnt(0)
	v_add_f32_e32 v161, v161, v165
	v_xor_b32_e32 v165, 32, v230
	v_cmp_lt_i32_e32 vcc, v165, v169
	s_nop 1
	v_cndmask_b32_e32 v165, v230, v165, vcc
	v_lshlrev_b32_e32 v165, 2, v165
	ds_bpermute_b32 v165, v165, v161
	s_waitcnt lgkmcnt(0)
	v_add_f32_e32 v161, v161, v165
	v_fmamk_f32 v161, v161, 0x3c800000, v226
	v_rsq_f32_e32 v220, v161
	s_nop 0

.LBB0_212:
	s_nop 0
	v_pk_mul_f32 v[130:131], v[48:49], v[164:165] op_sel_hi:[1,0]
	v_pk_mul_f32 v[132:133], v[46:47], v[164:165] op_sel_hi:[1,0]
	v_pk_mul_f32 v[134:135], v[44:45], v[164:165] op_sel_hi:[1,0]
	v_pk_mul_f32 v[136:137], v[42:43], v[164:165] op_sel_hi:[1,0]
	v_pk_mul_f32 v[212:213], v[40:41], v[164:165] op_sel_hi:[1,0]
	v_pk_mul_f32 v[214:215], v[38:39], v[164:165] op_sel_hi:[1,0]
	v_pk_mul_f32 v[208:209], v[36:37], v[164:165] op_sel_hi:[1,0]
	v_pk_mul_f32 v[210:211], v[34:35], v[164:165] op_sel_hi:[1,0]
	s_and_b64 vcc, exec, s[0:1]
	v_mov_b32_e32 v220, 1.0
	s_cbranch_vccnz .LBB0_214
	v_pk_mul_f32 v[216:217], v[130:131], v[130:131]
	v_pk_mul_f32 v[218:219], v[132:133], v[132:133]
	v_and_b32_e32 v169, 64, v230
	v_pk_mov_b32 v[220:221], v[218:219], v[216:217] op_sel:[1,0]
	v_mov_b32_e32 v219, v217
	v_pk_add_f32 v[216:217], v[220:221], v[218:219]
	v_pk_mul_f32 v[218:219], v[134:135], v[134:135]
	v_pk_add_f32 v[216:217], v[216:217], v[216:217] op_sel_hi:[0,1]
	v_pk_mul_f32 v[220:221], v[136:137], v[136:137]
	v_mul_f32_e32 v216, v214, v214
	v_pk_mov_b32 v[232:233], v[220:221], v[218:219] op_sel:[1,0]
	v_mov_b32_e32 v221, v219
	v_pk_add_f32 v[218:219], v[232:233], v[220:221]
	v_pk_fma_f32 v[220:221], v[214:215], v[214:215], v[216:217] op_sel_hi:[1,1,0]
	v_mul_f32_e32 v216, v212, v212
	v_pk_add_f32 v[218:219], v[218:219], v[218:219] op_sel_hi:[0,1]
	v_pk_fma_f32 v[232:233], v[212:213], v[212:213], v[216:217] op_sel_hi:[1,1,0]
	v_mul_f32_e32 v220, v210, v210
	v_mul_f32_e32 v232, v211, v211
	v_mul_f32_e32 v216, v208, v208
	v_mul_f32_e32 v218, v209, v209
	v_xor_b32_e32 v165, 16, v230
	v_add_u32_e32 v169, 64, v169
	v_pk_add_f32 v[220:221], v[220:221], v[232:233]
	v_pk_add_f32 v[216:217], v[216:217], v[218:219]
	v_cmp_lt_i32_e32 vcc, v165, v169
	v_pk_add_f32 v[216:217], v[220:221], v[216:217]
	s_nop 0
	v_cndmask_b32_e32 v165, v230, v165, vcc
	v_add_f32_e32 v161, v216, v217
	v_lshlrev_b32_e32 v165, 2, v165
	ds_bpermute_b32 v165, v165, v161
	s_waitcnt lgkmcnt(0)
	v_add_f32_e32 v161, v161, v165
	v_xor_b32_e32 v165, 32, v230
	v_cmp_lt_i32_e32 vcc, v165, v169
	s_nop 1
	v_cndmask_b32_e32 v165, v230, v165, vcc
	v_lshlrev_b32_e32 v165, 2, v165
	ds_bpermute_b32 v165, v165, v161
	s_waitcnt lgkmcnt(0)
	v_add_f32_e32 v161, v161, v165
	v_fmamk_f32 v161, v161, 0x3c800000, v226
	v_rsq_f32_e32 v220, v161
	s_nop 0

.LBB0_218:
	s_nop 0
	v_pk_mul_f32 v[130:131], v[32:33], v[160:161] op_sel_hi:[1,0]
	v_pk_mul_f32 v[132:133], v[30:31], v[160:161] op_sel_hi:[1,0]
	v_pk_mul_f32 v[134:135], v[28:29], v[160:161] op_sel_hi:[1,0]
	v_pk_mul_f32 v[136:137], v[26:27], v[160:161] op_sel_hi:[1,0]
	v_pk_mul_f32 v[212:213], v[24:25], v[160:161] op_sel_hi:[1,0]
	v_pk_mul_f32 v[214:215], v[22:23], v[160:161] op_sel_hi:[1,0]
	v_pk_mul_f32 v[208:209], v[20:21], v[160:161] op_sel_hi:[1,0]
	v_pk_mul_f32 v[210:211], v[18:19], v[160:161] op_sel_hi:[1,0]
	s_and_b64 vcc, exec, s[0:1]
	v_mov_b32_e32 v220, 1.0
	s_cbranch_vccnz .LBB0_220
	v_pk_mul_f32 v[216:217], v[130:131], v[130:131]
	v_pk_mul_f32 v[218:219], v[132:133], v[132:133]
	v_and_b32_e32 v169, 64, v230
	v_pk_mov_b32 v[220:221], v[218:219], v[216:217] op_sel:[1,0]
	v_mov_b32_e32 v219, v217
	v_pk_add_f32 v[216:217], v[220:221], v[218:219]
	v_pk_mul_f32 v[218:219], v[134:135], v[134:135]
	v_pk_add_f32 v[216:217], v[216:217], v[216:217] op_sel_hi:[0,1]
	v_pk_mul_f32 v[220:221], v[136:137], v[136:137]
	v_mul_f32_e32 v216, v214, v214
	v_pk_mov_b32 v[232:233], v[220:221], v[218:219] op_sel:[1,0]
	v_mov_b32_e32 v221, v219
	v_pk_add_f32 v[218:219], v[232:233], v[220:221]
	v_pk_fma_f32 v[220:221], v[214:215], v[214:215], v[216:217] op_sel_hi:[1,1,0]
	v_mul_f32_e32 v216, v212, v212
	v_pk_add_f32 v[218:219], v[218:219], v[218:219] op_sel_hi:[0,1]
	v_pk_fma_f32 v[232:233], v[212:213], v[212:213], v[216:217] op_sel_hi:[1,1,0]
	v_mul_f32_e32 v220, v210, v210
	v_mul_f32_e32 v232, v211, v211
	v_mul_f32_e32 v216, v208, v208
	v_mul_f32_e32 v218, v209, v209
	v_xor_b32_e32 v165, 16, v230
	v_add_u32_e32 v169, 64, v169
	v_pk_add_f32 v[220:221], v[220:221], v[232:233]
	v_pk_add_f32 v[216:217], v[216:217], v[218:219]
	v_cmp_lt_i32_e32 vcc, v165, v169
	v_pk_add_f32 v[216:217], v[220:221], v[216:217]
	s_nop 0
	v_cndmask_b32_e32 v165, v230, v165, vcc
	v_add_f32_e32 v161, v216, v217
	v_lshlrev_b32_e32 v165, 2, v165
	ds_bpermute_b32 v165, v165, v161
	s_waitcnt lgkmcnt(0)
	v_add_f32_e32 v161, v161, v165
	v_xor_b32_e32 v165, 32, v230
	v_cmp_lt_i32_e32 vcc, v165, v169
	s_nop 1
	v_cndmask_b32_e32 v165, v230, v165, vcc
	v_lshlrev_b32_e32 v165, 2, v165
	ds_bpermute_b32 v165, v165, v161
	s_waitcnt lgkmcnt(0)
	v_add_f32_e32 v161, v161, v165
	v_fmamk_f32 v161, v161, 0x3c800000, v226
	v_rsq_f32_e32 v220, v161
	s_nop 0

.LBB0_224:
	s_nop 0
	v_pk_mul_f32 v[130:131], v[16:17], v[156:157] op_sel_hi:[1,0]
	v_pk_mul_f32 v[132:133], v[14:15], v[156:157] op_sel_hi:[1,0]
	v_pk_mul_f32 v[134:135], v[12:13], v[156:157] op_sel_hi:[1,0]
	v_pk_mul_f32 v[136:137], v[10:11], v[156:157] op_sel_hi:[1,0]
	v_pk_mul_f32 v[212:213], v[8:9], v[156:157] op_sel_hi:[1,0]
	v_pk_mul_f32 v[214:215], v[6:7], v[156:157] op_sel_hi:[1,0]
	v_pk_mul_f32 v[208:209], v[4:5], v[156:157] op_sel_hi:[1,0]
	v_pk_mul_f32 v[210:211], v[2:3], v[156:157] op_sel_hi:[1,0]
	s_and_b64 vcc, exec, s[0:1]
	v_mov_b32_e32 v218, 1.0
	s_cbranch_vccnz .LBB0_226
	v_pk_mul_f32 v[216:217], v[130:131], v[130:131]
	v_pk_mul_f32 v[218:219], v[132:133], v[132:133]
	v_and_b32_e32 v169, 64, v230
	v_pk_mov_b32 v[220:221], v[218:219], v[216:217] op_sel:[1,0]
	v_mov_b32_e32 v219, v217
	v_pk_add_f32 v[216:217], v[220:221], v[218:219]
	v_pk_mul_f32 v[218:219], v[134:135], v[134:135]
	v_pk_add_f32 v[216:217], v[216:217], v[216:217] op_sel_hi:[0,1]
	v_pk_mul_f32 v[220:221], v[136:137], v[136:137]
	v_mul_f32_e32 v216, v214, v214
	v_pk_mov_b32 v[232:233], v[220:221], v[218:219] op_sel:[1,0]
	v_mov_b32_e32 v221, v219
	v_pk_add_f32 v[218:219], v[232:233], v[220:221]
	v_pk_fma_f32 v[220:221], v[214:215], v[214:215], v[216:217] op_sel_hi:[1,1,0]
	v_mul_f32_e32 v216, v212, v212
	v_pk_add_f32 v[218:219], v[218:219], v[218:219] op_sel_hi:[0,1]
	v_pk_fma_f32 v[232:233], v[212:213], v[212:213], v[216:217] op_sel_hi:[1,1,0]
	v_mul_f32_e32 v220, v210, v210
	v_mul_f32_e32 v232, v211, v211
	v_mul_f32_e32 v216, v208, v208
	v_mul_f32_e32 v218, v209, v209
	v_xor_b32_e32 v165, 16, v230
	v_add_u32_e32 v169, 64, v169
	v_pk_add_f32 v[220:221], v[220:221], v[232:233]
	v_pk_add_f32 v[216:217], v[216:217], v[218:219]
	v_cmp_lt_i32_e32 vcc, v165, v169
	v_pk_add_f32 v[216:217], v[220:221], v[216:217]
	s_nop 0
	v_cndmask_b32_e32 v165, v230, v165, vcc
	v_add_f32_e32 v161, v216, v217
	v_lshlrev_b32_e32 v165, 2, v165
	ds_bpermute_b32 v165, v165, v161
	s_waitcnt lgkmcnt(0)
	v_add_f32_e32 v161, v161, v165
	v_xor_b32_e32 v165, 32, v230
	v_cmp_lt_i32_e32 vcc, v165, v169
	s_nop 1
	v_cndmask_b32_e32 v165, v230, v165, vcc
	v_lshlrev_b32_e32 v165, 2, v165
	ds_bpermute_b32 v165, v165, v161
	s_waitcnt lgkmcnt(0)
	v_add_f32_e32 v161, v161, v165
	v_fmamk_f32 v161, v161, 0x3c800000, v226
	v_rsq_f32_e32 v218, v161
	s_nop 0
